# global attention KV loop rewritten by hand: K frags read up front, V frags prefetched behind QK MFMAs, exp/cvt interleaved with PV MFMAs, single 32-iteration loop
# speedup vs baseline: 1.0080x; 1.0080x over previous
;   DI u16* ob() const { return (u16*)(ws + OFF_ob); }
; DI float xhalf(float v) { return shx(v, 32, lane_opaque()); }
; template <int MODE>
; DI void attn_item(const Params& p, int layer, int b, int hq, int qb, u16* lds, const int WAVE_S) {
;     ...
;   const float lt = l_run + xhalf(l_run);
;   const float inv = 1.f / lt;
;   float ss = 0.f;
; #pragma unroll
;   for (int dt = 0; dt < 2; ++dt)
; #pragma unroll
;     for (int i = 0; i < 16; ++i) { o[dt][i] *= inv; ss += o[dt][i] * o[dt][i]; }
;   ss += xhalf(ss);
;   const float rs = rsqrtf(ss * (1.f / 64.f) + 1e-6f);
;   const float* gn = (MODE == 0 ? p.gn_a_g : p.gn_b_g) + layer * 512 + hq * 64;
;   u16* dst = p.ob() + ((size_t)b * SEQ + q0 + r) * DM + MODE * 512 + hq * 64;
; #pragma unroll
;   for (int dt = 0; dt < 2; ++dt)
; #pragma unroll
;     for (int g4 = 0; g4 < 4; ++g4) {
;       const int d = dt * 32 + 8 * g4 + 4 * h;
;       const float4 gg = *(const float4*)(gn + d);
;       *(uint2*)(dst + d) = make_uint2(pk2(o[dt][4 * g4 + 0] * rs * gg.x, o[dt][4 * g4 + 1] * rs * gg.y),
;                                       pk2(o[dt][4 * g4 + 2] * rs * gg.z, o[dt][4 * g4 + 3] * rs * gg.w));
;     }
.Lga_finalize:
	v_mbcnt_lo_u32_b32 v2, -1, 0
	v_mbcnt_hi_u32_b32 v2, -1, v2
	s_nop 0
	v_lshlrev_b32_e32 v2, 2, v2
	v_xor_b32_e32 v2, 0x80, v2
	ds_bpermute_b32 v2, v2, v0
	s_waitcnt lgkmcnt(0)
	v_add_f32_e32 v0, v0, v2
	v_div_scale_f32 v2, s[18:19], v0, v0, 1.0
	v_rcp_f32_e32 v3, v2
	s_lshl_b32 s18, s49, 8
	s_add_u32 s34, s47, s18
	s_addc_u32 s35, s48, 0
	v_fma_f32 v4, -v2, v3, 1.0
	v_fmac_f32_e32 v3, v4, v3
	v_div_scale_f32 v4, vcc, 1.0, v0, 1.0
	v_mul_f32_e32 v5, v4, v3
	v_fma_f32 v6, -v2, v5, v4
	v_fmac_f32_e32 v5, v6, v3
	v_fma_f32 v2, -v2, v5, v4
	v_div_fmas_f32 v2, v2, v3, v5
	s_lshl_b32 s28, s50, 11
	v_div_fixup_f32 v48, v2, v0, 1.0
	v_lshl_add_u64 v[2:3], s[28:29], 0, v[148:149]
	v_or_b32_e32 v2, v2, v156
	v_readlane_b32 s18, v165, 56
	v_lshlrev_b64 v[2:3], 11, v[2:3]
	v_readlane_b32 s19, v165, 57
	s_lshl_b32 s28, s49, 7
	v_pk_mul_f32 v[6:7], v[30:31], v[48:49] op_sel_hi:[1,0]
	v_lshl_add_u64 v[2:3], s[18:19], 0, v[2:3]
	v_mbcnt_lo_u32_b32 v0, -1, 0
	v_mbcnt_hi_u32_b32 v0, -1, v0
	v_lshl_add_u64 v[30:31], v[2:3], 0, s[28:29]
	global_load_dwordx4 v[2:5], v144, s[34:35]
	v_lshlrev_b32_e32 v0, 2, v0
	v_pk_mul_f32 v[10:11], v[26:27], v[48:49] op_sel_hi:[1,0]
	v_pk_mul_f32 v[8:9], v[28:29], v[48:49] op_sel_hi:[1,0]
	v_xor_b32_e32 v49, 0x80, v0
	v_pk_mul_f32 v[50:51], v[32:33], v[48:49] op_sel_hi:[1,0]
	v_pk_mul_f32 v[28:29], v[34:35], v[48:49] op_sel_hi:[1,0]
	v_pk_mul_f32 v[52:53], v[50:51], v[50:51]
	v_lshlrev_b32_e32 v0, 3, v163
	v_pk_mul_f32 v[34:35], v[28:29], v[28:29]
	v_lshl_add_u64 v[30:31], v[30:31], 0, v[0:1]
	v_add_f32_e32 v0, v52, v53
	v_pk_mul_f32 v[36:37], v[36:37], v[48:49] op_sel_hi:[1,0]
	v_add_f32_e32 v0, v34, v0
	v_pk_mul_f32 v[56:57], v[36:37], v[36:37]
	v_add_f32_e32 v0, v35, v0
	v_pk_mul_f32 v[38:39], v[38:39], v[48:49] op_sel_hi:[1,0]
	v_add_f32_e32 v0, v56, v0
	v_pk_mul_f32 v[54:55], v[38:39], v[38:39]
	v_add_f32_e32 v0, v57, v0
	v_pk_mul_f32 v[40:41], v[40:41], v[48:49] op_sel_hi:[1,0]
	v_add_f32_e32 v0, v54, v0
	v_pk_mul_f32 v[60:61], v[40:41], v[40:41]
	v_add_f32_e32 v0, v55, v0
	v_pk_mul_f32 v[42:43], v[42:43], v[48:49] op_sel_hi:[1,0]
	v_add_f32_e32 v0, v60, v0
	v_pk_mul_f32 v[58:59], v[42:43], v[42:43]
	v_add_f32_e32 v0, v61, v0
	v_pk_mul_f32 v[44:45], v[44:45], v[48:49] op_sel_hi:[1,0]
	v_add_f32_e32 v0, v58, v0
	v_pk_mul_f32 v[64:65], v[44:45], v[44:45]
	v_add_f32_e32 v0, v59, v0
	v_pk_mul_f32 v[46:47], v[46:47], v[48:49] op_sel_hi:[1,0]
	v_add_f32_e32 v0, v64, v0
	v_pk_mul_f32 v[62:63], v[46:47], v[46:47]
	v_add_f32_e32 v0, v65, v0
	v_pk_mul_f32 v[68:69], v[16:17], v[48:49] op_sel_hi:[1,0]
	v_add_f32_e32 v0, v62, v0
	v_pk_mul_f32 v[70:71], v[68:69], v[68:69]
	v_add_f32_e32 v0, v63, v0
	v_pk_mul_f32 v[32:33], v[18:19], v[48:49] op_sel_hi:[1,0]
	v_add_f32_e32 v0, v70, v0
	v_pk_mul_f32 v[66:67], v[32:33], v[32:33]
	v_add_f32_e32 v0, v71, v0
	v_pk_mul_f32 v[20:21], v[20:21], v[48:49] op_sel_hi:[1,0]
	v_add_f32_e32 v0, v66, v0
	v_pk_mul_f32 v[72:73], v[20:21], v[20:21]
	v_add_f32_e32 v0, v67, v0
	v_pk_mul_f32 v[18:19], v[22:23], v[48:49] op_sel_hi:[1,0]
	v_add_f32_e32 v0, v72, v0
	v_pk_mul_f32 v[22:23], v[18:19], v[18:19]
	v_add_f32_e32 v0, v73, v0
	v_pk_mul_f32 v[16:17], v[24:25], v[48:49] op_sel_hi:[1,0]
	v_add_f32_e32 v0, v22, v0
	v_pk_mul_f32 v[24:25], v[16:17], v[16:17]
	v_add_f32_e32 v0, v23, v0
	v_add_f32_e32 v0, v24, v0
	v_pk_mul_f32 v[12:13], v[10:11], v[10:11]
	v_add_f32_e32 v0, v25, v0
	v_add_f32_e32 v0, v12, v0
	v_pk_mul_f32 v[14:15], v[8:9], v[8:9]
	v_add_f32_e32 v0, v13, v0
	v_add_f32_e32 v0, v14, v0
	v_pk_mul_f32 v[26:27], v[6:7], v[6:7]
	v_add_f32_e32 v0, v15, v0
	v_add_f32_e32 v0, v26, v0
	v_add_f32_e32 v0, v27, v0
	ds_bpermute_b32 v12, v49, v0
	s_mov_b32 s18, 0x800000
	s_waitcnt lgkmcnt(0)
	v_add_f32_e32 v0, v0, v12
	v_mov_b32_e32 v12, 0x358637bd
	v_fmamk_f32 v0, v0, 0x3c800000, v12
	v_cmp_gt_f32_e32 vcc, s18, v0
	v_mul_f32_e32 v12, 0x4b800000, v0
	s_mov_b64 s[18:19], 0x70
	v_cndmask_b32_e32 v0, v0, v12, vcc
	v_rsq_f32_e32 v0, v0
	s_nop 0
	v_mul_f32_e32 v12, 0x45800000, v0
	v_cndmask_b32_e32 v0, v0, v12, vcc
	v_pk_mul_f32 v[12:13], v[50:51], v[0:1] op_sel_hi:[1,0]
	v_pk_mul_f32 v[10:11], v[10:11], v[0:1] op_sel_hi:[1,0]
	s_waitcnt vmcnt(0)
	v_pk_mul_f32 v[2:3], v[2:3], v[12:13]
	v_pk_mul_f32 v[12:13], v[28:29], v[0:1] op_sel_hi:[1,0]
	v_cvt_pk_bf16_f32 v2, v2, v3
	v_pk_mul_f32 v[4:5], v[4:5], v[12:13]
	v_pk_mul_f32 v[12:13], v[36:37], v[0:1] op_sel_hi:[1,0]
	v_cvt_pk_bf16_f32 v3, v4, v5
	global_store_dwordx2 v[30:31], v[2:3], off
	global_load_dwordx4 v[2:5], v144, s[34:35] offset:32
	v_pk_mul_f32 v[8:9], v[8:9], v[0:1] op_sel_hi:[1,0]
	s_waitcnt vmcnt(0)
	v_pk_mul_f32 v[2:3], v[2:3], v[12:13]
	v_pk_mul_f32 v[12:13], v[38:39], v[0:1] op_sel_hi:[1,0]
	v_cvt_pk_bf16_f32 v2, v2, v3
	v_pk_mul_f32 v[4:5], v[4:5], v[12:13]
	v_pk_mul_f32 v[12:13], v[40:41], v[0:1] op_sel_hi:[1,0]
	v_cvt_pk_bf16_f32 v3, v4, v5
	global_store_dwordx2 v[30:31], v[2:3], off offset:16
	global_load_dwordx4 v[2:5], v144, s[34:35] offset:64
	s_waitcnt vmcnt(0)
	v_pk_mul_f32 v[2:3], v[2:3], v[12:13]
	v_pk_mul_f32 v[12:13], v[42:43], v[0:1] op_sel_hi:[1,0]
	v_cvt_pk_bf16_f32 v2, v2, v3
	v_pk_mul_f32 v[4:5], v[4:5], v[12:13]
	v_pk_mul_f32 v[12:13], v[44:45], v[0:1] op_sel_hi:[1,0]
	v_cvt_pk_bf16_f32 v3, v4, v5
	global_store_dwordx2 v[30:31], v[2:3], off offset:32
	global_load_dwordx4 v[2:5], v144, s[34:35] offset:96
	s_waitcnt vmcnt(0)
	v_pk_mul_f32 v[2:3], v[2:3], v[12:13]
	v_pk_mul_f32 v[12:13], v[46:47], v[0:1] op_sel_hi:[1,0]
	v_cvt_pk_bf16_f32 v2, v2, v3
	v_pk_mul_f32 v[4:5], v[4:5], v[12:13]
	v_pk_mul_f32 v[12:13], v[68:69], v[0:1] op_sel_hi:[1,0]
	v_cvt_pk_bf16_f32 v3, v4, v5
	global_store_dwordx2 v[30:31], v[2:3], off offset:48
	global_load_dwordx4 v[2:5], v144, s[34:35] offset:128
	s_waitcnt vmcnt(0)
	v_pk_mul_f32 v[2:3], v[2:3], v[12:13]
	v_pk_mul_f32 v[12:13], v[32:33], v[0:1] op_sel_hi:[1,0]
	v_cvt_pk_bf16_f32 v2, v2, v3
	v_pk_mul_f32 v[4:5], v[4:5], v[12:13]
	v_pk_mul_f32 v[12:13], v[20:21], v[0:1] op_sel_hi:[1,0]
	v_cvt_pk_bf16_f32 v3, v4, v5
	global_store_dwordx2 v[30:31], v[2:3], off offset:64
	global_load_dwordx4 v[2:5], v144, s[34:35] offset:160
	s_waitcnt vmcnt(0)
	v_pk_mul_f32 v[2:3], v[2:3], v[12:13]
	v_pk_mul_f32 v[12:13], v[18:19], v[0:1] op_sel_hi:[1,0]
	v_cvt_pk_bf16_f32 v2, v2, v3
	v_pk_mul_f32 v[4:5], v[4:5], v[12:13]
	v_pk_mul_f32 v[12:13], v[16:17], v[0:1] op_sel_hi:[1,0]
	v_cvt_pk_bf16_f32 v3, v4, v5
	global_store_dwordx2 v[30:31], v[2:3], off offset:80
	global_load_dwordx4 v[2:5], v144, s[34:35] offset:192
	s_waitcnt vmcnt(0)
	v_pk_mul_f32 v[2:3], v[2:3], v[12:13]
	v_pk_mul_f32 v[4:5], v[4:5], v[10:11]
	v_cvt_pk_bf16_f32 v2, v2, v3
	v_cvt_pk_bf16_f32 v3, v4, v5
	global_store_dwordx2 v[30:31], v[2:3], off offset:96
	global_load_dwordx4 v[2:5], v144, s[34:35] offset:224
	s_waitcnt vmcnt(0)
	v_pk_mul_f32 v[2:3], v[2:3], v[8:9]
	s_nop 0
	v_cvt_pk_bf16_f32 v8, v2, v3
	v_pk_mul_f32 v[2:3], v[6:7], v[0:1] op_sel_hi:[1,0]
	v_lshl_add_u64 v[6:7], v[30:31], 0, s[18:19]
	v_pk_mul_f32 v[2:3], v[2:3], v[4:5]
	global_store_dword v[30:31], v8, off offset:112

;   DI u16* qbuf() const { return (u16*)(ws + OFF_qbuf); }
;   DI u16* kbuf() const { return (u16*)(ws + OFF_kbuf); }
; template <int MODE>
; DI void attn_item(const Params& p, int layer, int b, int hq, int qb, u16* lds, const int WAVE_S) {
;   const int tid = tid_opaque(), lane = tid & 63, wave = tid >> 6;
;   const int r = lane & 31, h = lane >> 5;
;   const int kvh = hq >> 2;
;   const int q0 = qb * 128 + wave * 32;
;   const u16* qp = p.qbuf() + (((size_t)(MODE * 32 + b) * 8 + hq) * SEQ + q0 + r) * 64;
;   const u16* kp = p.kbuf() + ((size_t)(MODE * 32 + b) * 2 + kvh) * SEQ * 64;
;   const u16* vp = p.vtbuf() + ((size_t)(MODE * 32 + b) * 2 + kvh) * 64 * SEQ;
;   bf16x8 qf[4];
; #pragma unroll
;   for (int ks = 0; ks < 4; ++ks) qf[ks] = *(const bf16x8*)(qp + ks * 16 + h * 8);
;   int t_begin, t_end, kbase0;
;   if (MODE == 0) { t_begin = 0; t_end = 32; kbase0 = 0; }
;   else { t_begin = (qb == 0) ? 2 : 0; t_end = (qb == 15) ? 4 : 6; kbase0 = qb * 128 - 128; }
;   float m_run, l_run;
;   float slope2 = 0.f;
;   if (MODE == 0) { m_run = 0.f; l_run = 0.f; }
;   else {
;     m_run = p.sink[layer * 8 + hq] * LOG2E;
;     l_run = (h == 0) ? 1.f : 0.f;
;     slope2 = exp2f(-(float)(hq + 1)) * LOG2E;
;   }
;   f32x16 negm;
; #pragma unroll
;   for (int i = 0; i < 16; ++i) negm[i] = -m_run;
;   f32x16 o[2];
; #pragma unroll
;   for (int dt = 0; dt < 2; ++dt)
; #pragma unroll
;     for (int i = 0; i < 16; ++i) o[dt][i] = 0.f;
;   const int lr = tid >> 3, lc = (tid & 7) * 8;
;   u32x4 kr[2], vr[2];
;   {
;     const int kb = kbase0 + t_begin * 64;
; #pragma unroll
;     for (int it = 0; it < 2; ++it) {
;       kr[it] = *(const u32x4*)(kp + (size_t)(kb + lr + 32 * it) * 64 + lc);
;       vr[it] = *(const u32x4*)(vp + (size_t)(lr + 32 * it) * SEQ + kb + lc);
;     }
;   }
;   __syncthreads();
;   {
;     u16* K0 = lds + (t_begin & 1) * 128 * LSTR;
; #pragma unroll
;     for (int it = 0; it < 2; ++it) {
;       *(u32x4*)(K0 + (lr + 32 * it) * LSTR + lc) = kr[it];
;       *(u32x4*)(K0 + 64 * LSTR + (lr + 32 * it) * LSTR + lc) = vr[it];
;     }
;     if (t_begin + 1 < t_end) {
;       const int kb = kbase0 + (t_begin + 1) * 64;
; #pragma unroll
;       for (int it = 0; it < 2; ++it) {
;         kr[it] = *(const u32x4*)(kp + (size_t)(kb + lr + 32 * it) * 64 + lc);
;         vr[it] = *(const u32x4*)(vp + (size_t)(lr + 32 * it) * SEQ + kb + lc);
;       }
;     }
;   }
.LBB0_190:
	s_and_b64 vcc, exec, s[18:19]
	s_cbranch_vccz .LBB0_170
	v_mbcnt_lo_u32_b32 v4, -1, 0
	v_mbcnt_hi_u32_b32 v4, -1, v4
	s_lshl_b32 s18, s50, 14
	v_add_u32_e32 v5, s33, v4
	v_ashrrev_i32_e32 v0, 1, v5
	s_lshl_b32 s19, s49, 11
	v_and_b32_e32 v156, 31, v4
	v_and_b32_e32 v0, 0xffffffe0, v0
	s_or_b32 s18, s18, s19
	v_add_u32_e32 v148, s36, v0
	v_or_b32_e32 v0, s18, v156
	s_lshl_b32 s28, s50, 19
	v_readlane_b32 s18, v166, 19
	s_or_b32 s34, s18, s28
	v_readlane_b32 s18, v164, 49
	v_readlane_b32 s19, v164, 50
	s_add_u32 s18, s18, s34
	v_ashrrev_i32_e32 v149, 31, v148
	s_addc_u32 s19, s19, 0
	v_readlane_b32 s35, v164, 53
	v_lshl_add_u64 v[2:3], v[0:1], 0, v[148:149]
	s_add_u32 s34, s35, s34
	v_readlane_b32 s35, v164, 54
	v_ashrrev_i32_e32 v32, 3, v5
	v_lshlrev_b32_e32 v0, 4, v4
	s_addc_u32 s35, s35, 0
	v_and_b32_e32 v0, 0x70, v0
	v_ashrrev_i32_e32 v33, 31, v32
	v_bfe_u32 v163, v4, 5, 1
	v_lshl_add_u64 v[4:5], s[18:19], 0, v[0:1]
	v_lshl_add_u64 v[6:7], s[34:35], 0, v[0:1]
	v_lshlrev_b64 v[34:35], 7, v[32:33]
	v_lshlrev_b64 v[36:37], 12, v[32:33]
	v_lshl_add_u64 v[8:9], v[4:5], 0, v[34:35]
	v_lshl_add_u64 v[10:11], v[6:7], 0, v[36:37]
	global_load_dwordx4 v[16:19], v[8:9], off
	global_load_dwordx4 v[20:23], v[10:11], off
	v_add_u32_e32 v10, 32, v32
	v_readlane_b32 s18, v164, 51
	v_lshlrev_b64 v[2:3], 7, v[2:3]
	v_ashrrev_i32_e32 v11, 31, v10
	v_readlane_b32 s19, v164, 52
	v_lshlrev_b64 v[12:13], 7, v[10:11]
	v_lshlrev_b32_e32 v144, 4, v163
	v_lshl_add_u64 v[2:3], s[18:19], 0, v[2:3]
	v_mov_b32_e32 v145, v1
	v_lshl_add_u64 v[4:5], v[4:5], 0, v[12:13]
	v_lshlrev_b64 v[10:11], 12, v[10:11]
	v_lshl_add_u64 v[2:3], v[2:3], 0, v[144:145]
	s_movk_i32 s18, 0x3000
	v_lshl_add_u64 v[6:7], v[6:7], 0, v[10:11]
	global_load_dwordx4 v[24:27], v[4:5], off
	global_load_dwordx4 v[28:31], v[6:7], off
	global_load_dwordx4 v[124:127], v[2:3], off
	global_load_dwordx4 v[120:123], v[2:3], off offset:32
	global_load_dwordx4 v[116:119], v[2:3], off offset:64
	global_load_dwordx4 v[112:115], v[2:3], off offset:96
	v_add_co_u32_e32 v2, vcc, s18, v8
	v_lshl_add_u64 v[4:5], s[34:35], 0, v[36:37]
	s_nop 0
	v_addc_co_u32_e32 v3, vcc, 0, v9, vcc
	s_barrier
	v_lshl_add_u64 v[4:5], v[4:5], 0, v[0:1]
	global_load_dwordx4 v[128:131], v[2:3], off offset:-4096
	global_load_dwordx4 v[132:135], v[2:3], off
	v_lshl_add_u64 v[2:3], s[34:35], 0, v[10:11]
	v_lshl_add_u64 v[2:3], v[2:3], 0, v[0:1]
	global_load_dwordx4 v[136:139], v[4:5], off offset:128
	global_load_dwordx4 v[140:143], v[2:3], off offset:128
	v_mad_u64_u32 v[150:151], s[18:19], v32, s13, v[0:1]
	v_lshl_add_u64 v[34:35], s[28:29], 0, v[34:35]
	v_readlane_b32 s18, v166, 24
	v_or_b32_e32 v34, v34, v0
	v_readlane_b32 s19, v166, 25
	v_lshl_add_u64 v[36:37], s[28:29], 0, v[36:37]
	v_mov_b32_e32 v14, v1
	v_lshl_add_u64 v[152:153], s[18:19], 0, v[34:35]
	v_readlane_b32 s18, v166, 22
	v_or_b32_e32 v36, v36, v0
	v_readlane_b32 s19, v166, 23
	v_mov_b32_e32 v15, v1
	v_mov_b32_e32 v2, v1
	v_mov_b32_e32 v3, v1
	v_mov_b32_e32 v4, v1
	v_mov_b32_e32 v5, v1
	v_mov_b32_e32 v6, v1
	v_mov_b32_e32 v7, v1
	v_mov_b32_e32 v8, v1
	v_mov_b32_e32 v9, v1
	v_mov_b32_e32 v10, v1
	v_mov_b32_e32 v11, v1
	v_mov_b32_e32 v12, v1
	v_mov_b32_e32 v13, v1
	v_mov_b32_e32 v0, v1
	v_lshl_add_u64 v[154:155], s[18:19], 0, v[36:37]
	v_bfrev_b32_e32 v64, 1
	s_waitcnt vmcnt(12)
	v_mov_b64_e32 v[46:47], v[14:15]
	v_mad_u32_u24 v145, v156, s13, v144
	v_mov_b32_e32 v151, 0
	s_waitcnt vmcnt(11)
	ds_write_b128 v150, v[16:19]
	s_waitcnt vmcnt(10)
	ds_write_b128 v150, v[20:23] offset:9216
	s_waitcnt vmcnt(9)
	ds_write_b128 v150, v[24:27] offset:4608
	s_waitcnt vmcnt(8)
	ds_write_b128 v150, v[28:31] offset:13824
	v_mov_b64_e32 v[30:31], v[14:15]
	s_mov_b64 s[34:35], 0
	v_mov_b64_e32 v[28:29], v[12:13]
	v_mov_b64_e32 v[26:27], v[10:11]
	v_mov_b64_e32 v[24:25], v[8:9]
	v_mov_b64_e32 v[22:23], v[6:7]
	v_mov_b64_e32 v[20:21], v[4:5]
	v_mov_b64_e32 v[18:19], v[2:3]
	v_mov_b64_e32 v[16:17], v[0:1]
	v_mov_b64_e32 v[44:45], v[12:13]
	v_mov_b64_e32 v[42:43], v[10:11]
	v_mov_b64_e32 v[40:41], v[8:9]
	v_mov_b64_e32 v[38:39], v[6:7]
	v_mov_b64_e32 v[36:37], v[4:5]
	v_mov_b64_e32 v[34:35], v[2:3]
	v_mov_b64_e32 v[32:33], v[0:1]
	v_mov_b32_e32 v0, 0
	v_mov_b32_e32 v65, v64
	v_mov_b32_e32 v66, v64
	v_mov_b32_e32 v67, v64
	v_mov_b32_e32 v68, v64
	v_mov_b32_e32 v69, v64
	v_mov_b32_e32 v70, v64
	v_mov_b32_e32 v71, v64
	v_mov_b32_e32 v72, v64
	v_mov_b32_e32 v73, v64
	v_mov_b32_e32 v74, v64
	v_mov_b32_e32 v75, v64
	v_mov_b32_e32 v76, v64
	v_mov_b32_e32 v77, v64
	v_mov_b32_e32 v78, v64
	v_mov_b32_e32 v79, v64
	s_waitcnt vmcnt(4)
	s_mov_b32 s18, 0x12000100
	s_mov_b32 s19, 0
	v_readfirstlane_b32 s60, v152
	v_readfirstlane_b32 s61, v153
	v_lshl_add_u64 v[154:155], v[154:155], 0, s[18:19]
	s_nop 1
	v_subrev_u32_e32 v152, s60, v152
	v_readfirstlane_b32 s62, v154
	v_readfirstlane_b32 s63, v155
	s_nop 1
	v_subrev_u32_e32 v153, s62, v154
	s_add_u32 s60, s60, 0x1000
	s_addc_u32 s61, s61, 0
	s_add_u32 s84, s62, 0x20000
	s_addc_u32 s85, s63, 0
	s_mov_b32 s34, 0
; template <int MODE>
; DI void attn_item(const Params& p, int layer, int b, int hq, int qb, u16* lds, const int WAVE_S) {
;     ...
;   for (int t = t_begin; t < t_end; ++t) {
;     __syncthreads();
;     const u16* Ks = lds + (t & 1) * 128 * LSTR;
;     const u16* Vs = Ks + 64 * LSTR;
;     if (t + 1 < t_end) {
;       u16* Kn = lds + ((t + 1) & 1) * 128 * LSTR;
; #pragma unroll
;       for (int it = 0; it < 2; ++it) {
;         *(u32x4*)(Kn + (lr + 32 * it) * LSTR + lc) = kr[it];
;         *(u32x4*)(Kn + 64 * LSTR + (lr + 32 * it) * LSTR + lc) = vr[it];
;       }
;       if (t + 2 < t_end) {
;         const int kb = kbase0 + (t + 2) * 64;
; #pragma unroll
;         for (int it = 0; it < 2; ++it) {
;           kr[it] = *(const u32x4*)(kp + (size_t)(kb + lr + 32 * it) * 64 + lc);
;           vr[it] = *(const u32x4*)(vp + (size_t)(lr + 32 * it) * SEQ + kb + lc);
;         }
;       }
;     }
;     bool live = true;
;     if (MODE == 1) {
;       const int kb = kbase0 + t * 64;
;       const int gap = (kb > q0 + 31) ? kb - (q0 + 31) : ((kb + 63 < q0) ? q0 - (kb + 63) : 0);
;       live = gap <= 128;
;     }
;     if (live) {
;     f32x16 sc[2];
; #pragma unroll
;     for (int k2 = 0; k2 < 2; ++k2) {
; #pragma unroll
;       for (int ks = 0; ks < 4; ++ks) {
;         const bf16x8 kf = *(const bf16x8*)(Ks + (k2 * 32 + r) * LSTR + ks * 16 + h * 8);
;         sc[k2] = (ks == 0) ? MFMA32(kf, qf[0], negm) : MFMA32(kf, qf[ks], sc[k2]);
;       }
;     }
;     if (MODE == 1) {
;       const float tposf = (float)(q0 + r - (kbase0 + t * 64) - 4 * h);
; #pragma unroll
;       for (int k2 = 0; k2 < 2; ++k2)
; #pragma unroll
;         for (int i = 0; i < 16; ++i) {
;           const float dist = fabsf(tposf - (float)(k2 * 32 + (i & 3) + 8 * (i >> 2)));
;           sc[k2][i] = (dist <= 128.f) ? (sc[k2][i] - slope2 * dist) : -1e30f;
;         }
;     }
;     float mx0 = fmaxf(fmaxf(sc[0][0], sc[0][1]), sc[0][2]), mx1 = fmaxf(fmaxf(sc[1][0], sc[1][1]), sc[1][2]);
; #pragma unroll
;     for (int i = 3; i < 15; i += 2) { mx0 = fmaxf(fmaxf(mx0, sc[0][i]), sc[0][i + 1]); mx1 = fmaxf(fmaxf(mx1, sc[1][i]), sc[1][i + 1]); }
;     float mx = fmaxf(fmaxf(mx0, mx1), fmaxf(sc[0][15], sc[1][15]));
;     {
;       auto rr = __builtin_amdgcn_permlane32_swap(__float_as_uint(mx), __float_as_uint(mx), false, false);
;       mx = fmaxf(__uint_as_float(rr[0]), __uint_as_float(rr[1]));
;     }
.Lga_loop:
	s_and_b32 s28, s34, 0x80
	s_mulk_i32 s28, 0x90
	v_add_u32_e32 v14, s28, v145
	s_xor_b32 s36, s28, 0x4800
	v_add_u32_e32 v15, s36, v150
	s_waitcnt lgkmcnt(0)
	s_barrier
	ds_read_b128 v[2:5], v14
	ds_read_b128 v[6:9], v14 offset:32
	ds_read_b128 v[10:13], v14 offset:64
	ds_read_b128 v[48:51], v14 offset:96
	ds_read_b128 v[52:55], v14 offset:4608
	ds_read_b128 v[56:59], v14 offset:4640
	ds_read_b128 v[60:63], v14 offset:4672
	ds_read_b128 v[158:161], v14 offset:4704
	s_waitcnt lgkmcnt(7)
	v_mfma_f32_32x32x16_bf16 v[96:111], v[2:5], v[124:127], v[64:79]
	ds_read_b128 v[2:5], v14 offset:9216
	s_waitcnt lgkmcnt(7)
	v_mfma_f32_32x32x16_bf16 v[96:111], v[6:9], v[120:123], v[96:111]
	ds_read_b128 v[6:9], v14 offset:9248
	s_waitcnt lgkmcnt(7)
	v_mfma_f32_32x32x16_bf16 v[96:111], v[10:13], v[116:119], v[96:111]
	ds_read_b128 v[10:13], v14 offset:9280
	s_waitcnt lgkmcnt(7)
	v_mfma_f32_32x32x16_bf16 v[96:111], v[48:51], v[112:115], v[96:111]
	ds_read_b128 v[48:51], v14 offset:9312
	s_waitcnt lgkmcnt(7)
	v_mfma_f32_32x32x16_bf16 v[80:95], v[52:55], v[124:127], v[64:79]
	ds_read_b128 v[52:55], v14 offset:13824
	s_waitcnt lgkmcnt(7)
	v_mfma_f32_32x32x16_bf16 v[80:95], v[56:59], v[120:123], v[80:95]
	ds_read_b128 v[56:59], v14 offset:13856
	s_waitcnt lgkmcnt(7)
	v_mfma_f32_32x32x16_bf16 v[80:95], v[60:63], v[116:119], v[80:95]
	ds_read_b128 v[60:63], v14 offset:13888
	s_waitcnt lgkmcnt(7)
	v_mfma_f32_32x32x16_bf16 v[80:95], v[158:161], v[112:115], v[80:95]
	ds_read_b128 v[158:161], v14 offset:13920
	v_max3_f32 v157, v96, v97, v98
	v_max3_f32 v157, v157, v99, v100
	v_max3_f32 v157, v157, v101, v102
	v_max3_f32 v157, v157, v103, v104
	v_max3_f32 v157, v157, v105, v106
	v_max3_f32 v157, v157, v107, v108
	v_max3_f32 v157, v157, v109, v110
	v_max_f32_e32 v157, v157, v111
	s_cmp_ge_u32 s34, 0xf80
	s_cbranch_scc1 .Lga_skipw
	s_waitcnt vmcnt(0)
	ds_write_b128 v15, v[128:131]
	ds_write_b128 v15, v[136:139] offset:9216
	ds_write_b128 v15, v[132:135] offset:4608
	ds_write_b128 v15, v[140:143] offset:13824
	s_cmp_ge_u32 s34, 0xf00
	s_cbranch_scc1 .Lga_skipw
	global_load_dwordx4 v[136:139], v153, s[62:63]
	global_load_dwordx4 v[128:131], v152, s[60:61] offset:-4096
	global_load_dwordx4 v[132:135], v152, s[60:61]
	global_load_dwordx4 v[140:143], v153, s[84:85]
	s_add_u32 s60, s60, s24
	s_addc_u32 s61, s61, s25
	s_add_u32 s62, s62, 0x80
	s_addc_u32 s63, s63, 0
	s_add_u32 s84, s84, 0x80
	s_addc_u32 s85, s85, 0
.Lga_skipw:
	s_nop 3
	v_max3_f32 v162, v80, v81, v82
	v_max3_f32 v162, v162, v83, v84
	v_max3_f32 v162, v162, v85, v86
	v_max3_f32 v162, v162, v87, v88
	v_max3_f32 v162, v162, v89, v90
	v_max3_f32 v162, v162, v91, v92
	v_max3_f32 v162, v162, v93, v94
	v_max3_f32 v157, v157, v162, v95
	v_mov_b32_e32 v162, v157
	s_nop 1
	v_permlane32_swap_b32_e32 v157, v162
	v_max_f32_e32 v157, v157, v162
	v_cmp_lt_f32_e32 vcc, s90, v157
	s_cbranch_vccnz .Lga_rescale
; #define MFMA32(a, b, c) __builtin_amdgcn_mfma_f32_32x32x16_bf16((a), (b), (c), 0, 0, 0)
; template <int MODE>
; DI void attn_item(const Params& p, int layer, int b, int hq, int qb, u16* lds, const int WAVE_S) {
;     ...
;     if (__any(mx > 8.0f)) {
;       const float delta = fmaxf(mx, 0.f);
;       const float al = __builtin_amdgcn_exp2f(-delta);
; #pragma unroll
;       for (int k2 = 0; k2 < 2; ++k2)
; #pragma unroll
;         for (int i = 0; i < 16; ++i) sc[k2][i] -= delta;
; #pragma unroll
;       for (int dt = 0; dt < 2; ++dt)
; #pragma unroll
;         for (int i = 0; i < 16; ++i) o[dt][i] *= al;
;       l_run *= al;
;       m_run += delta;
; #pragma unroll
;       for (int i = 0; i < 16; ++i) negm[i] = -m_run;
;     }
;     f32x2_t ps2 = {0.f, 0.f};
; #pragma unroll
;     for (int k2 = 0; k2 < 2; ++k2)
; #pragma unroll
;       for (int i = 0; i < 16; i += 2) {
;         const float e0 = __builtin_amdgcn_exp2f(sc[k2][i]), e1 = __builtin_amdgcn_exp2f(sc[k2][i + 1]);
;         sc[k2][i] = e0;
;         sc[k2][i + 1] = e1;
;         ps2 += (f32x2_t){e0, e1};
;       }
;     l_run += ps2[0] + ps2[1];
;     bf16x8 pf[2][2];
; #pragma unroll
;     for (int k2 = 0; k2 < 2; ++k2)
; #pragma unroll
;       for (int st = 0; st < 2; ++st) pf[k2][st] = pack8(sc[k2], st);
; #pragma unroll
;     for (int dt = 0; dt < 2; ++dt)
; #pragma unroll
;       for (int k2 = 0; k2 < 2; ++k2)
; #pragma unroll
;         for (int st = 0; st < 2; ++st) {
;           const bf16x8 vf = *(const bf16x8*)(Vs + (dt * 32 + r) * LSTR + k2 * 32 + st * 16 + h * 8);
;           o[dt] = MFMA32(vf, pf[k2][st], o[dt]);
;         }
;     __builtin_amdgcn_iglp_opt(1);
;     }
.Lga_exp:
	v_exp_f32_e32 v96, v96
	v_exp_f32_e32 v97, v97
	v_exp_f32_e32 v98, v98
	v_exp_f32_e32 v99, v99
	v_exp_f32_e32 v100, v100
	v_exp_f32_e32 v101, v101
	v_exp_f32_e32 v102, v102
	v_exp_f32_e32 v103, v103
	v_pk_add_f32 v[14:15], v[96:97], v[98:99]
	v_pk_add_f32 v[154:155], v[100:101], v[102:103]
	v_cvt_pk_bf16_f32 v96, v96, v97
	v_cvt_pk_bf16_f32 v97, v98, v99
	v_cvt_pk_bf16_f32 v98, v100, v101
	v_cvt_pk_bf16_f32 v99, v102, v103
	v_exp_f32_e32 v104, v104
	v_exp_f32_e32 v105, v105
	s_waitcnt lgkmcnt(0)
	v_mfma_f32_32x32x16_bf16 v[32:47], v[2:5], v[96:99], v[32:47]
	v_exp_f32_e32 v106, v106
	v_exp_f32_e32 v107, v107
	v_exp_f32_e32 v108, v108
	v_exp_f32_e32 v109, v109
	v_exp_f32_e32 v110, v110
	v_exp_f32_e32 v111, v111
	v_mfma_f32_32x32x16_bf16 v[16:31], v[52:55], v[96:99], v[16:31]
	v_pk_add_f32 v[14:15], v[14:15], v[104:105]
	v_pk_add_f32 v[154:155], v[154:155], v[106:107]
	v_pk_add_f32 v[14:15], v[14:15], v[108:109]
	v_pk_add_f32 v[154:155], v[154:155], v[110:111]
	v_cvt_pk_bf16_f32 v104, v104, v105
	v_cvt_pk_bf16_f32 v105, v106, v107
	v_cvt_pk_bf16_f32 v106, v108, v109
	v_cvt_pk_bf16_f32 v107, v110, v111
	v_exp_f32_e32 v80, v80
	v_exp_f32_e32 v81, v81
	v_mfma_f32_32x32x16_bf16 v[32:47], v[6:9], v[104:107], v[32:47]
	v_exp_f32_e32 v82, v82
	v_exp_f32_e32 v83, v83
	v_exp_f32_e32 v84, v84
	v_exp_f32_e32 v85, v85
	v_exp_f32_e32 v86, v86
	v_exp_f32_e32 v87, v87
	v_mfma_f32_32x32x16_bf16 v[16:31], v[56:59], v[104:107], v[16:31]
	v_pk_add_f32 v[14:15], v[14:15], v[80:81]
	v_pk_add_f32 v[154:155], v[154:155], v[82:83]
	v_pk_add_f32 v[14:15], v[14:15], v[84:85]
	v_pk_add_f32 v[154:155], v[154:155], v[86:87]
	v_cvt_pk_bf16_f32 v80, v80, v81
	v_cvt_pk_bf16_f32 v81, v82, v83
	v_cvt_pk_bf16_f32 v82, v84, v85
	v_cvt_pk_bf16_f32 v83, v86, v87
	v_exp_f32_e32 v88, v88
	v_exp_f32_e32 v89, v89
	v_mfma_f32_32x32x16_bf16 v[32:47], v[10:13], v[80:83], v[32:47]
	v_exp_f32_e32 v90, v90
	v_exp_f32_e32 v91, v91
	v_exp_f32_e32 v92, v92
	v_exp_f32_e32 v93, v93
	v_exp_f32_e32 v94, v94
	v_exp_f32_e32 v95, v95
	v_mfma_f32_32x32x16_bf16 v[16:31], v[60:63], v[80:83], v[16:31]
	v_pk_add_f32 v[14:15], v[14:15], v[88:89]
	v_pk_add_f32 v[154:155], v[154:155], v[90:91]
	v_pk_add_f32 v[14:15], v[14:15], v[92:93]
	v_pk_add_f32 v[154:155], v[154:155], v[94:95]
	v_cvt_pk_bf16_f32 v88, v88, v89
	v_cvt_pk_bf16_f32 v89, v90, v91
	v_cvt_pk_bf16_f32 v90, v92, v93
	v_cvt_pk_bf16_f32 v91, v94, v95
	v_pk_add_f32 v[14:15], v[14:15], v[154:155]
	s_add_u32 s34, s34, 0x80
	v_mfma_f32_32x32x16_bf16 v[32:47], v[48:51], v[88:91], v[32:47]
	v_add_f32_e32 v14, v14, v15
	s_cmp_lg_u32 s34, 0x1000
	v_mfma_f32_32x32x16_bf16 v[16:31], v[158:161], v[88:91], v[16:31]
	v_add_f32_e32 v0, v0, v14
	s_cbranch_scc1 .Lga_loop
	s_branch .Lga_finalize
.Lga_rescale:
	v_max_f32_e32 v157, 0, v157
	v_exp_f32_e64 v162, -v157
	v_add_f32_e32 v151, v151, v157
	v_sub_f32_e32 v96, v96, v157
	v_sub_f32_e32 v97, v97, v157
	v_sub_f32_e32 v98, v98, v157
	v_sub_f32_e32 v99, v99, v157
	v_sub_f32_e32 v100, v100, v157
	v_sub_f32_e32 v101, v101, v157
	v_sub_f32_e32 v102, v102, v157
	v_sub_f32_e32 v103, v103, v157
	v_sub_f32_e32 v104, v104, v157
	v_sub_f32_e32 v105, v105, v157
	v_sub_f32_e32 v106, v106, v157
	v_sub_f32_e32 v107, v107, v157
	v_sub_f32_e32 v108, v108, v157
	v_sub_f32_e32 v109, v109, v157
	v_sub_f32_e32 v110, v110, v157
	v_sub_f32_e32 v111, v111, v157
	v_sub_f32_e32 v80, v80, v157
	v_sub_f32_e32 v81, v81, v157
	v_sub_f32_e32 v82, v82, v157
	v_sub_f32_e32 v83, v83, v157
	v_sub_f32_e32 v84, v84, v157
	v_sub_f32_e32 v85, v85, v157
	v_sub_f32_e32 v86, v86, v157
	v_sub_f32_e32 v87, v87, v157
	v_sub_f32_e32 v88, v88, v157
	v_sub_f32_e32 v89, v89, v157
	v_sub_f32_e32 v90, v90, v157
	v_sub_f32_e32 v91, v91, v157
	v_sub_f32_e32 v92, v92, v157
	v_sub_f32_e32 v93, v93, v157
	v_sub_f32_e32 v94, v94, v157
	v_sub_f32_e32 v95, v95, v157
	v_mul_f32_e32 v16, v16, v162
	v_mul_f32_e32 v17, v17, v162
	v_mul_f32_e32 v18, v18, v162
	v_mul_f32_e32 v19, v19, v162
	v_mul_f32_e32 v20, v20, v162
	v_mul_f32_e32 v21, v21, v162
	v_mul_f32_e32 v22, v22, v162
	v_mul_f32_e32 v23, v23, v162
	v_mul_f32_e32 v24, v24, v162
	v_mul_f32_e32 v25, v25, v162
	v_mul_f32_e32 v26, v26, v162
	v_mul_f32_e32 v27, v27, v162
	v_mul_f32_e32 v28, v28, v162
	v_mul_f32_e32 v29, v29, v162
	v_mul_f32_e32 v30, v30, v162
	v_mul_f32_e32 v31, v31, v162
	v_mul_f32_e32 v32, v32, v162
	v_mul_f32_e32 v33, v33, v162
	v_mul_f32_e32 v34, v34, v162
	v_mul_f32_e32 v35, v35, v162
	v_mul_f32_e32 v36, v36, v162
	v_mul_f32_e32 v37, v37, v162
	v_mul_f32_e32 v38, v38, v162
	v_mul_f32_e32 v39, v39, v162
	v_mul_f32_e32 v40, v40, v162
	v_mul_f32_e32 v41, v41, v162
	v_mul_f32_e32 v42, v42, v162
	v_mul_f32_e32 v43, v43, v162
	v_mul_f32_e32 v44, v44, v162
	v_mul_f32_e32 v45, v45, v162
	v_mul_f32_e32 v46, v46, v162
	v_mul_f32_e32 v47, v47, v162
	v_mul_f32_e32 v0, v0, v162
	v_xor_b32_e32 v64, 0x80000000, v151
	s_nop 0
	v_mov_b32_e32 v65, v64
	v_mov_b32_e32 v66, v64
	v_mov_b32_e32 v67, v64
	v_mov_b32_e32 v68, v64
	v_mov_b32_e32 v69, v64
	v_mov_b32_e32 v70, v64
	v_mov_b32_e32 v71, v64
	v_mov_b32_e32 v72, v64
	v_mov_b32_e32 v73, v64
	v_mov_b32_e32 v74, v64
	v_mov_b32_e32 v75, v64
	v_mov_b32_e32 v76, v64
	v_mov_b32_e32 v77, v64
	v_mov_b32_e32 v78, v64
	v_mov_b32_e32 v79, v64
	s_branch .Lga_exp
